# up-projection sample-row small GEMM: row sum-of-squares lane exchanges (xor 1/2/4/8) via DPP moves instead of ds_bpermute, on top of the in-projection one
# baseline (speedup 1.0000x reference)
;     ...
;         if (AF32) {
; #pragma unroll
;             for (int i = 0; i < 8; ++i) { float q = q8[i]; q += __shfl_xor(q, 1); q += __shfl_xor(q, 2); q += __shfl_xor(q, 4); q += __shfl_xor(q, 8);
;                 if ((lane & 15) == 0) SSP[wave * 32 + 4 * i + (lane >> 4)] = q; }
;         }
.LBB0_1251:
	v_and_b32_e32 v37, 64, v205
	v_xor_b32_e32 v36, 1, v205
	v_add_u32_e32 v38, 64, v37
	v_cmp_lt_i32_e32 vcc, v36, v38
	v_xor_b32_e32 v37, 2, v205
	v_xor_b32_e32 v41, 8, v205
	v_cndmask_b32_e32 v36, v205, v36, vcc
	v_lshlrev_b32_e32 v36, 2, v36
	s_nop 1
	v_mov_b32_dpp v39, v34 quad_perm:[1,0,3,2] row_mask:0xf bank_mask:0xf
	v_cmp_lt_i32_e32 vcc, v37, v38
	s_waitcnt lgkmcnt(0)
	v_add_f32_e32 v39, v34, v39
	v_cndmask_b32_e32 v37, v205, v37, vcc
	v_lshlrev_b32_e32 v37, 2, v37
	s_nop 1
	v_mov_b32_dpp v40, v39 quad_perm:[2,3,0,1] row_mask:0xf bank_mask:0xf
	v_xor_b32_e32 v34, 4, v205
	v_cmp_lt_i32_e32 vcc, v34, v38
	s_waitcnt lgkmcnt(0)
	v_add_f32_e32 v39, v39, v40
	v_cndmask_b32_e32 v34, v205, v34, vcc
	v_lshlrev_b32_e32 v34, 2, v34
	s_nop 1
	v_mov_b32_dpp v40, v39 row_half_mirror row_mask:0xf bank_mask:0xf
	v_cmp_lt_i32_e32 vcc, v41, v38
	s_waitcnt lgkmcnt(0)
	v_add_f32_e32 v39, v39, v40
	v_cndmask_b32_e32 v38, v205, v41, vcc
	v_lshlrev_b32_e32 v38, 2, v38
	s_nop 1
	v_mov_b32_dpp v40, v39 row_mirror row_mask:0xf bank_mask:0xf
	s_and_saveexec_b64 s[22:23], s[10:11]
	s_cbranch_execz .LBB0_1253
	s_waitcnt lgkmcnt(0)
	v_add_f32_e32 v39, v39, v40
	ds_write_b32 v133, v39
.LBB0_1253:
	s_or_b64 exec, exec, s[22:23]
	s_nop 1
	v_mov_b32_dpp v39, v35 quad_perm:[1,0,3,2] row_mask:0xf bank_mask:0xf
	s_waitcnt lgkmcnt(0)
	v_add_f32_e32 v35, v35, v39
	s_nop 1
	v_mov_b32_dpp v39, v35 quad_perm:[2,3,0,1] row_mask:0xf bank_mask:0xf
	s_waitcnt lgkmcnt(0)
	v_add_f32_e32 v35, v35, v39
	s_nop 1
	v_mov_b32_dpp v39, v35 row_half_mirror row_mask:0xf bank_mask:0xf
	s_waitcnt lgkmcnt(0)
	v_add_f32_e32 v35, v35, v39
	s_nop 1
	v_mov_b32_dpp v39, v35 row_mirror row_mask:0xf bank_mask:0xf
	s_and_saveexec_b64 s[22:23], s[10:11]
	s_cbranch_execz .LBB0_1255
	s_waitcnt lgkmcnt(0)
	v_add_f32_e32 v35, v35, v39
	ds_write_b32 v133, v35 offset:16
.LBB0_1255:
	s_or_b64 exec, exec, s[22:23]
	s_nop 1
	v_mov_b32_dpp v35, v42 quad_perm:[1,0,3,2] row_mask:0xf bank_mask:0xf
	s_waitcnt lgkmcnt(0)
	v_add_f32_e32 v35, v42, v35
	s_nop 1
	v_mov_b32_dpp v39, v35 quad_perm:[2,3,0,1] row_mask:0xf bank_mask:0xf
	s_waitcnt lgkmcnt(0)
	v_add_f32_e32 v35, v35, v39
	s_nop 1
	v_mov_b32_dpp v39, v35 row_half_mirror row_mask:0xf bank_mask:0xf
	s_waitcnt lgkmcnt(0)
	v_add_f32_e32 v35, v35, v39
	s_nop 1
	v_mov_b32_dpp v39, v35 row_mirror row_mask:0xf bank_mask:0xf
	s_and_saveexec_b64 s[22:23], s[10:11]
	s_cbranch_execz .LBB0_1257
	s_waitcnt lgkmcnt(0)
	v_add_f32_e32 v35, v35, v39
	ds_write_b32 v133, v35 offset:32
.LBB0_1257:
	s_or_b64 exec, exec, s[22:23]
	s_nop 1
	v_mov_b32_dpp v35, v43 quad_perm:[1,0,3,2] row_mask:0xf bank_mask:0xf
	s_waitcnt lgkmcnt(0)
	v_add_f32_e32 v35, v43, v35
	s_nop 1
	v_mov_b32_dpp v39, v35 quad_perm:[2,3,0,1] row_mask:0xf bank_mask:0xf
	s_waitcnt lgkmcnt(0)
	v_add_f32_e32 v35, v35, v39
	s_nop 1
	v_mov_b32_dpp v39, v35 row_half_mirror row_mask:0xf bank_mask:0xf
	s_waitcnt lgkmcnt(0)
	v_add_f32_e32 v35, v35, v39
	s_nop 1
	v_mov_b32_dpp v39, v35 row_mirror row_mask:0xf bank_mask:0xf
	s_and_saveexec_b64 s[22:23], s[10:11]
	s_cbranch_execz .LBB0_1259
	s_waitcnt lgkmcnt(0)
	v_add_f32_e32 v35, v35, v39
	ds_write_b32 v133, v35 offset:48
.LBB0_1259:
	s_or_b64 exec, exec, s[22:23]
	s_nop 1
	v_mov_b32_dpp v35, v50 quad_perm:[1,0,3,2] row_mask:0xf bank_mask:0xf
	s_waitcnt lgkmcnt(0)
	v_add_f32_e32 v35, v50, v35
	s_nop 1
	v_mov_b32_dpp v39, v35 quad_perm:[2,3,0,1] row_mask:0xf bank_mask:0xf
	s_waitcnt lgkmcnt(0)
	v_add_f32_e32 v35, v35, v39
	s_nop 1
	v_mov_b32_dpp v39, v35 row_half_mirror row_mask:0xf bank_mask:0xf
	s_waitcnt lgkmcnt(0)
	v_add_f32_e32 v35, v35, v39
	s_nop 1
	v_mov_b32_dpp v39, v35 row_mirror row_mask:0xf bank_mask:0xf
	s_and_saveexec_b64 s[22:23], s[10:11]
	s_cbranch_execz .LBB0_1261
	s_waitcnt lgkmcnt(0)
	v_add_f32_e32 v35, v35, v39
	ds_write_b32 v133, v35 offset:64
.LBB0_1261:
	s_or_b64 exec, exec, s[22:23]
	s_nop 1
	v_mov_b32_dpp v35, v51 quad_perm:[1,0,3,2] row_mask:0xf bank_mask:0xf
	s_waitcnt lgkmcnt(0)
	v_add_f32_e32 v35, v51, v35
	s_nop 1
	v_mov_b32_dpp v39, v35 quad_perm:[2,3,0,1] row_mask:0xf bank_mask:0xf
	s_waitcnt lgkmcnt(0)
	v_add_f32_e32 v35, v35, v39
	s_nop 1
	v_mov_b32_dpp v39, v35 row_half_mirror row_mask:0xf bank_mask:0xf
	s_waitcnt lgkmcnt(0)
	v_add_f32_e32 v35, v35, v39
	s_nop 1
	v_mov_b32_dpp v39, v35 row_mirror row_mask:0xf bank_mask:0xf
	s_and_saveexec_b64 s[22:23], s[10:11]
	s_cbranch_execz .LBB0_1263
	s_waitcnt lgkmcnt(0)
	v_add_f32_e32 v35, v35, v39
	ds_write_b32 v133, v35 offset:80
.LBB0_1263:
	s_or_b64 exec, exec, s[22:23]
	s_nop 1
	v_mov_b32_dpp v35, v58 quad_perm:[1,0,3,2] row_mask:0xf bank_mask:0xf
	s_waitcnt lgkmcnt(0)
	v_add_f32_e32 v35, v58, v35
	s_nop 1
	v_mov_b32_dpp v39, v35 quad_perm:[2,3,0,1] row_mask:0xf bank_mask:0xf
	s_waitcnt lgkmcnt(0)
	v_add_f32_e32 v35, v35, v39
	s_nop 1
	v_mov_b32_dpp v39, v35 row_half_mirror row_mask:0xf bank_mask:0xf
	s_waitcnt lgkmcnt(0)
	v_add_f32_e32 v35, v35, v39
	s_nop 1
	v_mov_b32_dpp v39, v35 row_mirror row_mask:0xf bank_mask:0xf
	s_and_saveexec_b64 s[22:23], s[10:11]
	s_cbranch_execz .LBB0_1265
	s_waitcnt lgkmcnt(0)
	v_add_f32_e32 v35, v35, v39
	ds_write_b32 v133, v35 offset:96
.LBB0_1265:
	s_or_b64 exec, exec, s[22:23]
	s_nop 1
	v_mov_b32_dpp v35, v59 quad_perm:[1,0,3,2] row_mask:0xf bank_mask:0xf
	s_waitcnt lgkmcnt(0)
	v_add_f32_e32 v35, v59, v35
	s_nop 1
	v_mov_b32_dpp v36, v35 quad_perm:[2,3,0,1] row_mask:0xf bank_mask:0xf
	s_waitcnt lgkmcnt(0)
	v_add_f32_e32 v35, v35, v36
	s_nop 1
	v_mov_b32_dpp v34, v35 row_half_mirror row_mask:0xf bank_mask:0xf
	s_waitcnt lgkmcnt(0)
	v_add_f32_e32 v34, v35, v34
	s_nop 1
	v_mov_b32_dpp v35, v34 row_mirror row_mask:0xf bank_mask:0xf
	s_and_saveexec_b64 s[22:23], s[10:11]
	s_cbranch_execz .LBB0_1267
	s_waitcnt lgkmcnt(0)
	v_add_f32_e32 v34, v34, v35
	ds_write_b32 v133, v34 offset:112
